# gdn_prep 16x16 diagonal solve: L rows read once per wave, elements via v_readlane SGPR operands, rows paired for two interleaved chains
# baseline (speedup 1.0000x reference)
; DI void phase_gdn_prep(const Params& p, int l, char* smem) {
;     ...
;             if (rb > 0) {
;                 const int j = tid & 127, rh = tid >> 7;
;                 float* X = (j < 64) ? sv : sk; const int col = j & 63;
;                 const int r0 = rb * 16 + rh * 8;
;                 float a[8];
; #pragma unroll
;                 for (int i = 0; i < 8; ++i) a[i] = 0.f;
;                 for (int s4 = 0; s4 < rb * 16; s4 += 4) {
;                     const float x0 = X[(s4 + 0) * 65 + col], x1 = X[(s4 + 1) * 65 + col], x2 = X[(s4 + 2) * 65 + col], x3 = X[(s4 + 3) * 65 + col];
; #pragma unroll
;                     for (int i = 0; i < 8; ++i) {
;                         const f32x4 lv = *(const f32x4*)(sL + (r0 + i) * 64 + s4);
;                         a[i] += lv[0] * x0 + lv[1] * x1 + lv[2] * x2 + lv[3] * x3;
;                     }
;                 }
; #pragma unroll
;                 for (int i = 0; i < 8; ++i) X[(r0 + i) * 65 + col] -= a[i];
;     ...
;             if (tid < 128) {
;                 float* X = (tid < 64) ? sv : sk; const int col = tid & 63;
;                 float x[16];
; #pragma unroll
;                 for (int i = 0; i < 16; ++i) x[i] = X[(rb * 16 + i) * 65 + col];
; #pragma unroll
;                 for (int i = 1; i < 16; ++i) {
;                     const float* Lr = sL + (rb * 16 + i) * 64 + rb * 16;
.LBB0_335:
	s_cmp_eq_u32 s4, 0
	s_cbranch_scc0 .Lgd_dense
	s_mul_i32 s5, s4, 0x1040
	s_add_i32 s5, s5, 0xc300
	v_and_b32_e32 v186, 15, v62
	v_lshl_add_u32 v186, v186, 2, s5
	ds_read_b32 v36, v186 offset:256
	ds_read_b32 v37, v186 offset:512
	ds_read_b32 v38, v186 offset:768
	ds_read_b32 v39, v186 offset:1024
	ds_read_b32 v58, v186 offset:1280
	ds_read_b32 v59, v186 offset:1536
	ds_read_b32 v60, v186 offset:1792
	ds_read_b32 v61, v186 offset:2048
	ds_read_b32 v230, v186 offset:2304
	ds_read_b32 v231, v186 offset:2560
	ds_read_b32 v232, v186 offset:2816
	ds_read_b32 v233, v186 offset:3072
	ds_read_b32 v234, v186 offset:3328
	ds_read_b32 v235, v186 offset:3584
	ds_read_b32 v236, v186 offset:3840
	s_branch .LBB0_339
.Lgd_dense:
	v_and_b32_e32 v204, 15, v62
	v_lshrrev_b32_e32 v205, 4, v62
	v_lshlrev_b32_e32 v186, 8, v204
	v_lshl_add_u32 v186, v205, 4, v186
	s_lshl_b32 s5, s4, 12
	s_add_i32 s5, s5, 0xc300
	v_add_u32_e32 v186, s5, v186
	v_mul_u32_u24_e32 v187, 0x410, v205
	v_lshl_add_u32 v187, v204, 2, v187
	v_and_b32_e32 v206, 64, v40
	v_lshl_add_u32 v187, v206, 1, v187
	v_mov_b32_e32 v206, 0x8200
	v_mov_b32_e32 v207, 0x4100
	s_mul_i32 s5, s4, 0x1040
	v_cndmask_b32_e64 v206, v207, v206, s[48:49]
	v_add_u32_e32 v187, v187, v206
	v_add_u32_e32 v188, s5, v187
	ds_read_b128 v[192:195], v186 offset:0
	ds_read_b32 v196, v187 offset:0
	ds_read_b32 v197, v187 offset:64
	ds_read_b32 v198, v187 offset:260
	ds_read_b32 v199, v187 offset:324
	ds_read_b32 v200, v187 offset:520
	ds_read_b32 v201, v187 offset:584
	ds_read_b32 v202, v187 offset:780
	ds_read_b32 v203, v187 offset:844
	s_cmp_lt_u32 s4, 2
	s_cbranch_scc1 .Lgd_1
	ds_read_b128 v[36:39], v186 offset:64
	ds_read_b32 v58, v187 offset:4160
	ds_read_b32 v59, v187 offset:4224
	ds_read_b32 v60, v187 offset:4420
	ds_read_b32 v61, v187 offset:4484
	ds_read_b32 v204, v187 offset:4680
	ds_read_b32 v205, v187 offset:4744
	ds_read_b32 v206, v187 offset:4940
	ds_read_b32 v207, v187 offset:5004
	s_waitcnt lgkmcnt(9)
	v_mfma_f32_16x16x4_f32 v[230:233], v192, v196, 0
	v_mfma_f32_16x16x4_f32 v[234:237], v192, v197, 0
	v_mfma_f32_16x16x4_f32 v[230:233], v193, v198, v[230:233]
	v_mfma_f32_16x16x4_f32 v[234:237], v193, v199, v[234:237]
	v_mfma_f32_16x16x4_f32 v[230:233], v194, v200, v[230:233]
	v_mfma_f32_16x16x4_f32 v[234:237], v194, v201, v[234:237]
	v_mfma_f32_16x16x4_f32 v[230:233], v195, v202, v[230:233]
	v_mfma_f32_16x16x4_f32 v[234:237], v195, v203, v[234:237]
	s_cmp_lt_u32 s4, 3
	s_cbranch_scc1 .Lgd_2
	ds_read_b128 v[192:195], v186 offset:128
	ds_read_b32 v196, v187 offset:8320
	ds_read_b32 v197, v187 offset:8384
	ds_read_b32 v198, v187 offset:8580
	ds_read_b32 v199, v187 offset:8644
	ds_read_b32 v200, v187 offset:8840
	ds_read_b32 v201, v187 offset:8904
	ds_read_b32 v202, v187 offset:9100
	ds_read_b32 v203, v187 offset:9164
	s_waitcnt lgkmcnt(9)
	v_mfma_f32_16x16x4_f32 v[230:233], v36, v58, v[230:233]
	v_mfma_f32_16x16x4_f32 v[234:237], v36, v59, v[234:237]
	v_mfma_f32_16x16x4_f32 v[230:233], v37, v60, v[230:233]
	v_mfma_f32_16x16x4_f32 v[234:237], v37, v61, v[234:237]
	v_mfma_f32_16x16x4_f32 v[230:233], v38, v204, v[230:233]
	v_mfma_f32_16x16x4_f32 v[234:237], v38, v205, v[234:237]
	v_mfma_f32_16x16x4_f32 v[230:233], v39, v206, v[230:233]
	v_mfma_f32_16x16x4_f32 v[234:237], v39, v207, v[234:237]
	s_waitcnt lgkmcnt(0)
	v_mfma_f32_16x16x4_f32 v[230:233], v192, v196, v[230:233]
	v_mfma_f32_16x16x4_f32 v[234:237], v192, v197, v[234:237]
	v_mfma_f32_16x16x4_f32 v[230:233], v193, v198, v[230:233]
	v_mfma_f32_16x16x4_f32 v[234:237], v193, v199, v[234:237]
	v_mfma_f32_16x16x4_f32 v[230:233], v194, v200, v[230:233]
	v_mfma_f32_16x16x4_f32 v[234:237], v194, v201, v[234:237]
	v_mfma_f32_16x16x4_f32 v[230:233], v195, v202, v[230:233]
	v_mfma_f32_16x16x4_f32 v[234:237], v195, v203, v[234:237]
	s_branch .Lgd_upd

; DI void phase_gdn_prep(const Params& p, int l, char* smem) {
;     ...
;                 for (int i = 0; i < 8; ++i) X[(r0 + i) * 65 + col] -= a[i];
;                 __syncthreads();
;             }
;             if (tid < 128) {
;                 float* X = (tid < 64) ? sv : sk; const int col = tid & 63;
;                 float x[16];
; #pragma unroll
;                 for (int i = 0; i < 16; ++i) x[i] = X[(rb * 16 + i) * 65 + col];
; #pragma unroll
;                 for (int i = 1; i < 16; ++i) {
;                     const float* Lr = sL + (rb * 16 + i) * 64 + rb * 16;
;                     float acc = x[i];
; #pragma unroll
;                     for (int s2 = 0; s2 < i; ++s2) acc -= Lr[s2] * x[s2];
;                     x[i] = acc;
;                 }
; #pragma unroll
;                 for (int i = 1; i < 16; ++i) X[(rb * 16 + i) * 65 + col] = x[i];
.Lgd_upd:
	ds_read_b32 v196, v188 offset:0
	ds_read_b32 v197, v188 offset:260
	ds_read_b32 v198, v188 offset:520
	ds_read_b32 v199, v188 offset:780
	ds_read_b32 v200, v188 offset:64
	ds_read_b32 v201, v188 offset:324
	ds_read_b32 v202, v188 offset:584
	ds_read_b32 v203, v188 offset:844
	s_nop 4
	s_waitcnt lgkmcnt(0)
	v_sub_f32_e32 v196, v196, v230
	v_sub_f32_e32 v197, v197, v231
	v_sub_f32_e32 v198, v198, v232
	v_sub_f32_e32 v199, v199, v233
	v_sub_f32_e32 v200, v200, v234
	v_sub_f32_e32 v201, v201, v235
	v_sub_f32_e32 v202, v202, v236
	v_sub_f32_e32 v203, v203, v237
	s_mul_i32 s5, s4, 0x1040
	s_add_i32 s5, s5, 0xc300
	v_and_b32_e32 v186, 15, v62
	v_lshl_add_u32 v186, v186, 2, s5
	ds_read_b32 v36, v186 offset:256
	ds_read_b32 v37, v186 offset:512
	ds_read_b32 v38, v186 offset:768
	ds_read_b32 v39, v186 offset:1024
	ds_read_b32 v58, v186 offset:1280
	ds_read_b32 v59, v186 offset:1536
	ds_read_b32 v60, v186 offset:1792
	ds_read_b32 v61, v186 offset:2048
	ds_read_b32 v230, v186 offset:2304
	ds_read_b32 v231, v186 offset:2560
	ds_read_b32 v232, v186 offset:2816
	ds_read_b32 v233, v186 offset:3072
	ds_read_b32 v234, v186 offset:3328
	ds_read_b32 v235, v186 offset:3584
	ds_read_b32 v236, v186 offset:3840
	ds_write_b32 v188, v196 offset:0
	ds_write_b32 v188, v197 offset:260
	ds_write_b32 v188, v198 offset:520
	ds_write_b32 v188, v199 offset:780
	ds_write_b32 v188, v200 offset:64
	ds_write_b32 v188, v201 offset:324
	ds_write_b32 v188, v202 offset:584
	ds_write_b32 v188, v203 offset:844
	s_waitcnt lgkmcnt(0)
	s_barrier
.LBB0_339:
	s_and_saveexec_b64 s[86:87], s[48:49]
	s_cbranch_execz .LBB0_334
	s_mul_i32 s5, s4, 0x1040
	v_add_u32_e32 v191, s5, v77
	ds_read_b32 v192, v191
	ds_read_b32 v193, v191 offset:260
	ds_read_b32 v194, v191 offset:520
	ds_read_b32 v195, v191 offset:780
	ds_read_b32 v196, v191 offset:1040
	ds_read_b32 v197, v191 offset:1300
	ds_read_b32 v198, v191 offset:1560
	ds_read_b32 v199, v191 offset:1820
	ds_read_b32 v200, v191 offset:2080
	ds_read_b32 v201, v191 offset:2340
	ds_read_b32 v202, v191 offset:2600
	ds_read_b32 v203, v191 offset:2860
	ds_read_b32 v204, v191 offset:3120
	ds_read_b32 v205, v191 offset:3380
	ds_read_b32 v206, v191 offset:3640
	ds_read_b32 v207, v191 offset:3900
	s_waitcnt lgkmcnt(0)
	v_readlane_b32 s98, v36, 0
	v_readlane_b32 s99, v37, 0
	v_readlane_b32 s100, v37, 1
	v_readlane_b32 s101, v38, 0
	v_fma_f32 v193, -v192, s98, v193
	v_readlane_b32 s6, v39, 0
	v_fma_f32 v194, -v192, s99, v194
	v_readlane_b32 s7, v38, 1
	v_fma_f32 v194, -v193, s100, v194
	v_readlane_b32 s98, v39, 1
	v_fma_f32 v195, -v192, s101, v195
	v_readlane_b32 s99, v38, 2
	v_fma_f32 v196, -v192, s6, v196
	v_readlane_b32 s100, v39, 2
	v_fma_f32 v195, -v193, s7, v195
	v_readlane_b32 s101, v39, 3
	v_fma_f32 v196, -v193, s98, v196
	v_readlane_b32 s6, v58, 0
	v_fma_f32 v195, -v194, s99, v195
	v_readlane_b32 s7, v59, 0
	v_fma_f32 v196, -v194, s100, v196
	v_readlane_b32 s98, v58, 1
	v_fma_f32 v196, -v195, s101, v196
	v_readlane_b32 s99, v59, 1
	v_fma_f32 v197, -v192, s6, v197
	v_readlane_b32 s100, v58, 2
	v_fma_f32 v198, -v192, s7, v198
	v_readlane_b32 s101, v59, 2
	v_fma_f32 v197, -v193, s98, v197
	v_readlane_b32 s6, v58, 3
	v_fma_f32 v198, -v193, s99, v198
	v_readlane_b32 s7, v59, 3
	v_fma_f32 v197, -v194, s100, v197
	v_readlane_b32 s98, v58, 4
	v_fma_f32 v198, -v194, s101, v198
	v_readlane_b32 s99, v59, 4
	v_fma_f32 v197, -v195, s6, v197
	v_readlane_b32 s100, v59, 5
	v_fma_f32 v198, -v195, s7, v198
	v_readlane_b32 s101, v60, 0
	v_fma_f32 v197, -v196, s98, v197
	v_readlane_b32 s6, v61, 0
	v_fma_f32 v198, -v196, s99, v198
	v_readlane_b32 s7, v60, 1
	v_fma_f32 v198, -v197, s100, v198
	v_readlane_b32 s98, v61, 1
	v_fma_f32 v199, -v192, s101, v199
	v_readlane_b32 s99, v60, 2
	v_fma_f32 v200, -v192, s6, v200
	v_readlane_b32 s100, v61, 2
	v_fma_f32 v199, -v193, s7, v199
	v_readlane_b32 s101, v60, 3
	v_fma_f32 v200, -v193, s98, v200
	v_readlane_b32 s6, v61, 3
	v_fma_f32 v199, -v194, s99, v199
	v_readlane_b32 s7, v60, 4
	v_fma_f32 v200, -v194, s100, v200
	v_readlane_b32 s98, v61, 4
	v_fma_f32 v199, -v195, s101, v199
	v_readlane_b32 s99, v60, 5
	v_fma_f32 v200, -v195, s6, v200
	v_readlane_b32 s100, v61, 5
	v_fma_f32 v199, -v196, s7, v199
	v_readlane_b32 s101, v60, 6
	v_fma_f32 v200, -v196, s98, v200
	v_readlane_b32 s6, v61, 6
	v_fma_f32 v199, -v197, s99, v199
	v_readlane_b32 s7, v61, 7
	v_fma_f32 v200, -v197, s100, v200
	v_readlane_b32 s98, v230, 0
	v_fma_f32 v199, -v198, s101, v199
	v_readlane_b32 s99, v231, 0
	v_fma_f32 v200, -v198, s6, v200
	v_readlane_b32 s100, v230, 1
	v_fma_f32 v200, -v199, s7, v200
	v_readlane_b32 s101, v231, 1
	v_fma_f32 v201, -v192, s98, v201
	v_readlane_b32 s6, v230, 2
	v_fma_f32 v202, -v192, s99, v202
	v_readlane_b32 s7, v231, 2
	v_fma_f32 v201, -v193, s100, v201
	v_readlane_b32 s98, v230, 3
	v_fma_f32 v202, -v193, s101, v202
	v_readlane_b32 s99, v231, 3
	v_fma_f32 v201, -v194, s6, v201
	v_readlane_b32 s100, v230, 4
	v_fma_f32 v202, -v194, s7, v202
	v_readlane_b32 s101, v231, 4
	v_fma_f32 v201, -v195, s98, v201
	v_readlane_b32 s6, v230, 5
	v_fma_f32 v202, -v195, s99, v202
	v_readlane_b32 s7, v231, 5
	v_fma_f32 v201, -v196, s100, v201
	v_readlane_b32 s98, v230, 6
; DI void phase_gdn_prep(const Params& p, int l, char* smem) {
;     ...
;             if (tid < 128) {
;                 float* X = (tid < 64) ? sv : sk; const int col = tid & 63;
;                 float x[16];
; #pragma unroll
;                 for (int i = 0; i < 16; ++i) x[i] = X[(rb * 16 + i) * 65 + col];
; #pragma unroll
;                 for (int i = 1; i < 16; ++i) {
;                     const float* Lr = sL + (rb * 16 + i) * 64 + rb * 16;
;                     float acc = x[i];
; #pragma unroll
;                     for (int s2 = 0; s2 < i; ++s2) acc -= Lr[s2] * x[s2];
;                     x[i] = acc;
;                 }
; #pragma unroll
;                 for (int i = 1; i < 16; ++i) X[(rb * 16 + i) * 65 + col] = x[i];
;             }
	v_fma_f32 v202, -v196, s101, v202
	v_readlane_b32 s99, v231, 6
	v_fma_f32 v201, -v197, s6, v201
	v_readlane_b32 s100, v230, 7
	v_fma_f32 v202, -v197, s7, v202
	v_readlane_b32 s101, v231, 7
	v_fma_f32 v201, -v198, s98, v201
	v_readlane_b32 s6, v230, 8
	v_fma_f32 v202, -v198, s99, v202
	v_readlane_b32 s7, v231, 8
	v_fma_f32 v201, -v199, s100, v201
	v_readlane_b32 s98, v231, 9
	v_fma_f32 v202, -v199, s101, v202
	v_readlane_b32 s99, v232, 0
	v_fma_f32 v201, -v200, s6, v201
	v_readlane_b32 s100, v233, 0
	v_fma_f32 v202, -v200, s7, v202
	v_readlane_b32 s101, v232, 1
	v_fma_f32 v202, -v201, s98, v202
	v_readlane_b32 s6, v233, 1
	v_fma_f32 v203, -v192, s99, v203
	v_readlane_b32 s7, v232, 2
	v_fma_f32 v204, -v192, s100, v204
	v_readlane_b32 s98, v233, 2
	v_fma_f32 v203, -v193, s101, v203
	v_readlane_b32 s99, v232, 3
	v_fma_f32 v204, -v193, s6, v204
	v_readlane_b32 s100, v233, 3
	v_fma_f32 v203, -v194, s7, v203
	v_readlane_b32 s101, v232, 4
	v_fma_f32 v204, -v194, s98, v204
	v_readlane_b32 s6, v233, 4
	v_fma_f32 v203, -v195, s99, v203
	v_readlane_b32 s7, v232, 5
	v_fma_f32 v204, -v195, s100, v204
	v_readlane_b32 s98, v233, 5
	v_fma_f32 v203, -v196, s101, v203
	v_readlane_b32 s99, v232, 6
	v_fma_f32 v204, -v196, s6, v204
	v_readlane_b32 s100, v233, 6
	v_fma_f32 v203, -v197, s7, v203
	v_readlane_b32 s101, v232, 7
	v_fma_f32 v204, -v197, s98, v204
	v_readlane_b32 s6, v233, 7
	v_fma_f32 v203, -v198, s99, v203
	v_readlane_b32 s7, v232, 8
	v_fma_f32 v204, -v198, s100, v204
	v_readlane_b32 s98, v233, 8
	v_fma_f32 v203, -v199, s101, v203
	v_readlane_b32 s99, v232, 9
	v_fma_f32 v204, -v199, s6, v204
	v_readlane_b32 s100, v233, 9
	v_fma_f32 v203, -v200, s7, v203
	v_readlane_b32 s101, v232, 10
	v_fma_f32 v204, -v200, s98, v204
	v_readlane_b32 s6, v233, 10
	v_fma_f32 v203, -v201, s99, v203
	v_readlane_b32 s7, v233, 11
	v_fma_f32 v204, -v201, s100, v204
	v_readlane_b32 s98, v234, 0
	v_fma_f32 v203, -v202, s101, v203
	v_readlane_b32 s99, v235, 0
	v_fma_f32 v204, -v202, s6, v204
	v_readlane_b32 s100, v234, 1
	v_fma_f32 v204, -v203, s7, v204
	v_readlane_b32 s101, v235, 1
	v_fma_f32 v205, -v192, s98, v205
	v_readlane_b32 s6, v234, 2
	v_fma_f32 v206, -v192, s99, v206
	v_readlane_b32 s7, v235, 2
	v_fma_f32 v205, -v193, s100, v205
	v_readlane_b32 s98, v234, 3
	v_fma_f32 v206, -v193, s101, v206
	v_readlane_b32 s99, v235, 3
	v_fma_f32 v205, -v194, s6, v205
	v_readlane_b32 s100, v234, 4
	v_fma_f32 v206, -v194, s7, v206
	v_readlane_b32 s101, v235, 4
	v_fma_f32 v205, -v195, s98, v205
	v_readlane_b32 s6, v234, 5
	v_fma_f32 v206, -v195, s99, v206
	v_readlane_b32 s7, v235, 5
	v_fma_f32 v205, -v196, s100, v205
	v_readlane_b32 s98, v234, 6
	v_fma_f32 v206, -v196, s101, v206
	v_readlane_b32 s99, v235, 6
	v_fma_f32 v205, -v197, s6, v205
	v_readlane_b32 s100, v234, 7
	v_fma_f32 v206, -v197, s7, v206
	v_readlane_b32 s101, v235, 7
	v_fma_f32 v205, -v198, s98, v205
	v_readlane_b32 s6, v234, 8
	v_fma_f32 v206, -v198, s99, v206
	v_readlane_b32 s7, v235, 8
	v_fma_f32 v205, -v199, s100, v205
	v_readlane_b32 s98, v234, 9
	v_fma_f32 v206, -v199, s101, v206
	v_readlane_b32 s99, v235, 9
	v_fma_f32 v205, -v200, s6, v205
	v_readlane_b32 s100, v234, 10
	v_fma_f32 v206, -v200, s7, v206
	v_readlane_b32 s101, v235, 10
	v_fma_f32 v205, -v201, s98, v205
	v_readlane_b32 s6, v234, 11
	v_fma_f32 v206, -v201, s99, v206
	v_readlane_b32 s7, v235, 11
	v_fma_f32 v205, -v202, s100, v205
	v_readlane_b32 s98, v234, 12
	v_fma_f32 v206, -v202, s101, v206
	v_readlane_b32 s99, v235, 12
	v_fma_f32 v205, -v203, s6, v205
	v_readlane_b32 s100, v235, 13
	v_fma_f32 v206, -v203, s7, v206
	v_readlane_b32 s101, v236, 0
	v_fma_f32 v205, -v204, s98, v205
	v_readlane_b32 s6, v236, 1
	v_fma_f32 v206, -v204, s99, v206
	v_readlane_b32 s7, v236, 2
	v_fma_f32 v206, -v205, s100, v206
	v_readlane_b32 s98, v236, 3
	v_fma_f32 v207, -v192, s101, v207
	v_readlane_b32 s99, v236, 4
	v_fma_f32 v207, -v193, s6, v207
	v_readlane_b32 s100, v236, 5
	v_fma_f32 v207, -v194, s7, v207
	v_readlane_b32 s101, v236, 6
	v_fma_f32 v207, -v195, s98, v207
	v_readlane_b32 s6, v236, 7
	v_fma_f32 v207, -v196, s99, v207
	v_readlane_b32 s7, v236, 8
	v_fma_f32 v207, -v197, s100, v207
	v_readlane_b32 s98, v236, 9
	v_fma_f32 v207, -v198, s101, v207
	v_readlane_b32 s99, v236, 10
	v_fma_f32 v207, -v199, s6, v207
	v_readlane_b32 s100, v236, 11
	v_fma_f32 v207, -v200, s7, v207
	v_readlane_b32 s101, v236, 12
	v_fma_f32 v207, -v201, s98, v207
	v_readlane_b32 s6, v236, 13
	v_fma_f32 v207, -v202, s99, v207
	v_readlane_b32 s7, v236, 14
	v_fma_f32 v207, -v203, s100, v207
	v_fma_f32 v207, -v204, s101, v207
	v_fma_f32 v207, -v205, s6, v207
	v_fma_f32 v207, -v206, s7, v207
	ds_write_b32 v191, v193 offset:260
	ds_write_b32 v191, v194 offset:520
	ds_write_b32 v191, v195 offset:780
	ds_write_b32 v191, v196 offset:1040
	ds_write_b32 v191, v197 offset:1300
	ds_write_b32 v191, v198 offset:1560
	ds_write_b32 v191, v199 offset:1820
	ds_write_b32 v191, v200 offset:2080
	ds_write_b32 v191, v201 offset:2340
	ds_write_b32 v191, v202 offset:2600
	ds_write_b32 v191, v203 offset:2860
	ds_write_b32 v191, v204 offset:3120
	ds_write_b32 v191, v205 offset:3380
	ds_write_b32 v191, v206 offset:3640
	ds_write_b32 v191, v207 offset:3900
	s_branch .LBB0_334
